# EpiResid GEMM K-loops: one extra global_load_dword per wave per K-iteration touches 1/8 of the unit's residual XB tile (L2/MALL prefetch), vmcnt 8->9 on the three waits it rides under
# speedup vs baseline: 1.0049x; 1.0049x over previous
; #define PG8_STAGE(bufoff, gbase, voff) do { _Pragma("unroll") for (int _i = 0; _i < 2; ++_i) \
;         __builtin_amdgcn_global_load_lds((const unsigned*)((const char*)(gbase) + (voff)[_i]), (PG8_LAS unsigned*)(lds + (bufoff) + ldsw + _i * 8192), 16, 0, 0); } while (0)
; #define PG8_LDA(dst, b, h) do { _Pragma("unroll") for (int m = 0; m < 4; ++m) _Pragma("unroll") for (int k = 0; k < 2; ++k) dst[m][k] = *(const PG8_LAS bf16x8*)(lds + PG8_SA(b, h) + aoff + m * 2048 + k * 1024); } while (0)
; #define PG8_LDB(dst, b, h) do { _Pragma("unroll") for (int n = 0; n < 2; ++n) _Pragma("unroll") for (int k = 0; k < 2; ++k) dst[n][k] = *(const PG8_LAS bf16x8*)(lds + PG8_SB(b, h) + boff + n * 2048 + k * 1024); } while (0)
; #define PG8_BAR __builtin_amdgcn_s_barrier()
; #define PG8_SCHED __builtin_amdgcn_sched_barrier(0)
; template <class Epi, class Sched, bool ALIGN_EPI = false, bool SP2 = false>
; __device__ __forceinline__ void gemm_phase(PG8_LAS unsigned char* lds, const Gemm g, const Sched& S, const Epi& E) {
;     ...
;         const bool has_next = S.next(ui + 1, nxt);
;         const char* nA = has_next ? (const char*)g.A + (size_t)nxt.pm * tstep : cA; const char* nB = has_next ? (const char*)g.Bt + (size_t)nxt.pn * tstep : cB;
;         for (int t = 0; t < nt; t += 2) {
;             const bool last = (t == nt - 2);
;             const char* a1 = cA + (size_t)(t + 1) * kstep;
;             const char* a2 = last ? nA : cA + (size_t)(t + 2) * kstep; const char* b2 = last ? nB : cB + (size_t)(t + 2) * kstep;
;             const char* a3 = a2 + kstep; const char* b3 = b2 + kstep;
;             if (last && has_next) S.a_ready(nxt);
;             if constexpr (SP2) {
;             PG8_LDB(B0, 0, 0); PG8_LDB(B1, 0, 1); PG8_SCHED; PG8_LDA(At, 0, 0); PG8_STAGE(PG8_SA(1, 1), a1 + hstep, voffA);
;     ...
;         if constexpr (ALIGN_EPI) { if (wr == 0) PG8_BAR; }
;         if constexpr (!Epi::AFTER_DRAIN) { E(acc, cur, wr, wc, fr, fq); S.done(cur); }
;         if (!has_next) break;
; #pragma unroll
;         for (int a = 0; a < 2; ++a)
; #pragma unroll
;             for (int b = 0; b < 2; ++b)
; #pragma unroll
;                 for (int m = 0; m < 4; ++m)
; #pragma unroll
;                     for (int n = 0; n < 2; ++n) acc[a][b][m][n] = (f32x4){0.f, 0.f, 0.f, 0.f};
.LBB0_1679:
	s_ashr_i32 s23, s22, 31
	s_lshl_b64 s[4:5], s[22:23], 19
	s_add_u32 s24, s0, s4
	s_addc_u32 s25, s1, s5
	s_and_b64 s[4:5], s[10:11], exec
	s_cselect_b32 s23, s25, s29
	s_cselect_b32 s52, s24, s28
	s_ashr_i32 s21, s20, 31
	s_lshl_b64 s[4:5], s[20:21], 19
	s_add_u32 s26, s38, s4
	s_addc_u32 s27, s39, s5
	s_and_b64 s[4:5], s[10:11], exec
	s_cselect_b32 s21, s27, s31
	s_cselect_b32 s53, s26, s30
	s_add_u32 s54, s30, 0x100
	v_mov_b32_e32 v2, 0
	s_addc_u32 s55, s31, 0
	s_mov_b32 s64, -2
	s_waitcnt lgkmcnt(0)
	v_mov_b32_e32 v3, v2
	v_mov_b32_e32 v4, v2
	v_mov_b32_e32 v5, v2
	v_mov_b32_e32 v6, v2
	v_mov_b32_e32 v7, v2
	v_mov_b32_e32 v8, v2
	v_mov_b32_e32 v9, v2
	v_mov_b32_e32 v18, v2
	v_mov_b32_e32 v19, v2
	v_mov_b32_e32 v20, v2
	v_mov_b32_e32 v21, v2
	v_mov_b32_e32 v22, v2
	v_mov_b32_e32 v23, v2
	v_mov_b32_e32 v24, v2
	v_mov_b32_e32 v25, v2
	v_mov_b32_e32 v34, v2
	v_mov_b32_e32 v35, v2
	v_mov_b32_e32 v36, v2
	v_mov_b32_e32 v37, v2
	v_mov_b32_e32 v38, v2
	v_mov_b32_e32 v39, v2
	v_mov_b32_e32 v40, v2
	v_mov_b32_e32 v41, v2
	v_mov_b32_e32 v50, v2
	v_mov_b32_e32 v51, v2
	v_mov_b32_e32 v52, v2
	v_mov_b32_e32 v53, v2
	v_mov_b32_e32 v54, v2
	v_mov_b32_e32 v55, v2
	v_mov_b32_e32 v56, v2
	v_mov_b32_e32 v57, v2
	v_mov_b32_e32 v10, v2
	v_mov_b32_e32 v11, v2
	v_mov_b32_e32 v12, v2
	v_mov_b32_e32 v13, v2
	v_mov_b32_e32 v14, v2
	v_mov_b32_e32 v15, v2
	v_mov_b32_e32 v16, v2
	v_mov_b32_e32 v17, v2
	v_mov_b32_e32 v26, v2
	v_mov_b32_e32 v27, v2
	v_mov_b32_e32 v28, v2
	v_mov_b32_e32 v29, v2
	v_mov_b32_e32 v30, v2
	v_mov_b32_e32 v31, v2
	v_mov_b32_e32 v32, v2
	v_mov_b32_e32 v33, v2
	v_mov_b32_e32 v42, v2
	v_mov_b32_e32 v43, v2
	v_mov_b32_e32 v44, v2
	v_mov_b32_e32 v45, v2
	v_mov_b32_e32 v46, v2
	v_mov_b32_e32 v47, v2
	v_mov_b32_e32 v48, v2
	v_mov_b32_e32 v49, v2
	v_mov_b32_e32 v58, v2
	v_mov_b32_e32 v59, v2
	v_mov_b32_e32 v60, v2
	v_mov_b32_e32 v61, v2
	v_mov_b32_e32 v62, v2
	v_mov_b32_e32 v63, v2
	v_mov_b32_e32 v64, v2
	v_mov_b32_e32 v65, v2
	v_mov_b32_e32 v66, v2
	v_mov_b32_e32 v67, v2
	v_mov_b32_e32 v68, v2
	v_mov_b32_e32 v69, v2
	v_mov_b32_e32 v70, v2
	v_mov_b32_e32 v71, v2
	v_mov_b32_e32 v72, v2
	v_mov_b32_e32 v73, v2
	v_mov_b32_e32 v82, v2
	v_mov_b32_e32 v83, v2
	v_mov_b32_e32 v84, v2
	v_mov_b32_e32 v85, v2
	v_mov_b32_e32 v86, v2
	v_mov_b32_e32 v87, v2
	v_mov_b32_e32 v88, v2
	v_mov_b32_e32 v89, v2
	v_mov_b32_e32 v98, v2
	v_mov_b32_e32 v99, v2
	v_mov_b32_e32 v100, v2
	v_mov_b32_e32 v101, v2
	v_mov_b32_e32 v102, v2
	v_mov_b32_e32 v103, v2
	v_mov_b32_e32 v104, v2
	v_mov_b32_e32 v105, v2
	v_mov_b32_e32 v114, v2
	v_mov_b32_e32 v115, v2
	v_mov_b32_e32 v116, v2
	v_mov_b32_e32 v117, v2
	v_mov_b32_e32 v118, v2
	v_mov_b32_e32 v119, v2
	v_mov_b32_e32 v120, v2
	v_mov_b32_e32 v121, v2
	v_mov_b32_e32 v74, v2
	v_mov_b32_e32 v75, v2
	v_mov_b32_e32 v76, v2
	v_mov_b32_e32 v77, v2
	v_mov_b32_e32 v78, v2
	v_mov_b32_e32 v79, v2
	v_mov_b32_e32 v80, v2
	v_mov_b32_e32 v81, v2
	v_mov_b32_e32 v90, v2
	v_mov_b32_e32 v91, v2
	v_mov_b32_e32 v92, v2
	v_mov_b32_e32 v93, v2
	v_mov_b32_e32 v94, v2
	v_mov_b32_e32 v95, v2
	v_mov_b32_e32 v96, v2
	v_mov_b32_e32 v97, v2
	v_mov_b32_e32 v106, v2
	v_mov_b32_e32 v107, v2
	v_mov_b32_e32 v108, v2
	v_mov_b32_e32 v109, v2
	v_mov_b32_e32 v110, v2
	v_mov_b32_e32 v111, v2
	v_mov_b32_e32 v112, v2
	v_mov_b32_e32 v113, v2
	v_mov_b32_e32 v122, v2
	v_mov_b32_e32 v123, v2
	v_mov_b32_e32 v124, v2
	v_mov_b32_e32 v125, v2
	v_mov_b32_e32 v126, v2
	v_mov_b32_e32 v127, v2
	v_mov_b32_e32 v128, v2
	v_mov_b32_e32 v129, v2
	v_lshrrev_b32_e32 v249, 4, v190
	v_lshlrev_b32_e32 v249, 11, v249
	v_bfe_u32 v250, v190, 2, 2
	v_lshl_add_u32 v249, v250, 7, v249
	v_and_b32_e32 v250, 3, v190
	v_lshl_add_u32 v249, v250, 2, v249
	s_lshl_b32 s100, s41, 3
	s_lshl_b32 s101, s51, 19
	s_add_u32 s100, s100, s101
	s_lshl_b32 s101, s50, 9
	s_add_u32 s100, s100, s101
	v_add_u32_e32 v249, s100, v249
.LBB0_1680:
	s_add_u32 s30, s28, 0x100
	s_addc_u32 s31, s29, 0
	s_add_i32 s4, 0, 0x10000
	s_cmp_eq_u32 s64, 12
	s_cselect_b32 s37, s23, s31
	s_cselect_b32 s36, s52, s30
	v_add_u32_e32 v165, s4, v162
	s_cselect_b32 s35, s21, s55
	s_cselect_b32 s34, s53, s54
	s_add_i32 s65, 0, 0x14000
	ds_read_b128 v[158:161], v165
	ds_read_b128 v[166:169], v165 offset:1024
	ds_read_b128 v[170:173], v165 offset:2048
	ds_read_b128 v[174:177], v165 offset:3072
	v_add_u32_e32 v165, s65, v162
	ds_read_b128 v[178:181], v165
	ds_read_b128 v[182:185], v165 offset:1024
	ds_read_b128 v[186:189], v165 offset:2048
	ds_read_b128 v[202:205], v165 offset:3072
	v_lshl_add_u64 v[238:239], s[28:29], 0, v[154:155]
	s_add_i32 m0, s41, 0xc000
	ds_read_b128 v[206:209], v164
	ds_read_b128 v[210:213], v164 offset:1024
	ds_read_b128 v[214:217], v164 offset:2048
	ds_read_b128 v[218:221], v164 offset:3072
	ds_read_b128 v[222:225], v164 offset:4096
	ds_read_b128 v[226:229], v164 offset:5120
	ds_read_b128 v[230:233], v164 offset:6144
	ds_read_b128 v[234:237], v164 offset:7168
	global_load_lds_dwordx4 v[238:239], off
	v_lshl_add_u64 v[238:239], s[28:29], 0, v[156:157]
	s_add_i32 m0, s41, 0xe000
	s_nop 0
	global_load_lds_dwordx4 v[238:239], off
	s_bfe_u32 s100, s64, 0x30001
	s_lshl_b32 s100, s100, 16
	v_add_u32_e32 v250, s100, v249
	global_load_dword v248, v250, s[14:15]
	s_waitcnt vmcnt(9)
	s_waitcnt lgkmcnt(0)
	s_barrier
; #define PG8_STAGE(bufoff, gbase, voff) do { _Pragma("unroll") for (int _i = 0; _i < 2; ++_i) \
;         __builtin_amdgcn_global_load_lds((const unsigned*)((const char*)(gbase) + (voff)[_i]), (PG8_LAS unsigned*)(lds + (bufoff) + ldsw + _i * 8192), 16, 0, 0); } while (0)
; #define PG8_LDA(dst, b, h) do { _Pragma("unroll") for (int m = 0; m < 4; ++m) _Pragma("unroll") for (int k = 0; k < 2; ++k) dst[m][k] = *(const PG8_LAS bf16x8*)(lds + PG8_SA(b, h) + aoff + m * 2048 + k * 1024); } while (0)
; #define PG8_LDB(dst, b, h) do { _Pragma("unroll") for (int n = 0; n < 2; ++n) _Pragma("unroll") for (int k = 0; k < 2; ++k) dst[n][k] = *(const PG8_LAS bf16x8*)(lds + PG8_SB(b, h) + boff + n * 2048 + k * 1024); } while (0)
; #define PG8_MMA(ai, bj, At, Bt) do { __builtin_amdgcn_s_setprio(1); _Pragma("unroll") for (int m = 0; m < 4; ++m) _Pragma("unroll") for (int n = 0; n < 2; ++n) _Pragma("unroll") for (int k = 0; k < 2; ++k) \
;         acc[ai][bj][m][n] = __builtin_amdgcn_mfma_f32_16x16x32_bf16(Bt[n][k], At[m][k], acc[ai][bj][m][n], 0, 0, 0); __builtin_amdgcn_s_setprio(0); } while (0)
; #define PG8_WAIT_V(n) asm volatile("s_waitcnt vmcnt(" #n ")" ::: "memory")
; #define PG8_WAIT_L(n) asm volatile("s_waitcnt lgkmcnt(" #n ")" ::: "memory")
; #define PG8_BAR __builtin_amdgcn_s_barrier()
; #define PG8_SCHED __builtin_amdgcn_sched_barrier(0)
; template <class Epi, class Sched, bool ALIGN_EPI = false, bool SP2 = false>
; __device__ __forceinline__ void gemm_phase(PG8_LAS unsigned char* lds, const Gemm g, const Sched& S, const Epi& E) {
;     ...
;             PG8_LDB(B0, 0, 0); PG8_LDB(B1, 0, 1); PG8_SCHED; PG8_LDA(At, 0, 0); PG8_STAGE(PG8_SA(1, 1), a1 + hstep, voffA);
;             PG8_WAIT_V(8); PG8_WAIT_L(0); PG8_BAR; PG8_MMA(0, 0, At, B0); PG8_MMA(0, 1, At, B1); PG8_BAR; PG8_SCHED;
;             PG8_LDA(At, 0, 1); PG8_STAGE(PG8_SB(0, 0), b2, voffB); PG8_STAGE(PG8_SB(0, 1), b2 + hstep, voffB); PG8_STAGE(PG8_SA(0, 0), a2, voffA);
;             PG8_WAIT_V(8); PG8_WAIT_L(0); PG8_BAR; PG8_MMA(1, 0, At, B0); PG8_MMA(1, 1, At, B1); PG8_BAR; PG8_SCHED;
	s_setprio 1
	s_waitcnt lgkmcnt(0)
	v_mfma_f32_16x16x32_bf16 v[126:129], v[158:161], v[206:209], v[126:129]
	v_mfma_f32_16x16x32_bf16 v[122:125], v[170:173], v[206:209], v[122:125]
	v_mfma_f32_16x16x32_bf16 v[110:113], v[158:161], v[214:217], v[110:113]
	v_mfma_f32_16x16x32_bf16 v[106:109], v[170:173], v[214:217], v[106:109]
	v_mfma_f32_16x16x32_bf16 v[94:97], v[158:161], v[222:225], v[94:97]
	v_mfma_f32_16x16x32_bf16 v[90:93], v[170:173], v[222:225], v[90:93]
	v_mfma_f32_16x16x32_bf16 v[78:81], v[158:161], v[230:233], v[78:81]
	v_mfma_f32_16x16x32_bf16 v[74:77], v[170:173], v[230:233], v[74:77]
	v_mfma_f32_16x16x32_bf16 v[126:129], v[166:169], v[210:213], v[126:129]
	v_mfma_f32_16x16x32_bf16 v[122:125], v[174:177], v[210:213], v[122:125]
	v_mfma_f32_16x16x32_bf16 v[110:113], v[166:169], v[218:221], v[110:113]
	v_mfma_f32_16x16x32_bf16 v[106:109], v[174:177], v[218:221], v[106:109]
	v_mfma_f32_16x16x32_bf16 v[94:97], v[166:169], v[226:229], v[94:97]
	v_mfma_f32_16x16x32_bf16 v[90:93], v[174:177], v[226:229], v[90:93]
	v_mfma_f32_16x16x32_bf16 v[78:81], v[166:169], v[234:237], v[78:81]
	v_mfma_f32_16x16x32_bf16 v[74:77], v[174:177], v[234:237], v[74:77]
	s_setprio 0
	s_setprio 1
	v_mfma_f32_16x16x32_bf16 v[118:121], v[178:181], v[206:209], v[118:121]
	v_mfma_f32_16x16x32_bf16 v[114:117], v[186:189], v[206:209], v[114:117]
	v_mfma_f32_16x16x32_bf16 v[102:105], v[178:181], v[214:217], v[102:105]
	v_mfma_f32_16x16x32_bf16 v[98:101], v[186:189], v[214:217], v[98:101]
	v_mfma_f32_16x16x32_bf16 v[86:89], v[178:181], v[222:225], v[86:89]
	v_mfma_f32_16x16x32_bf16 v[82:85], v[186:189], v[222:225], v[82:85]
	v_mfma_f32_16x16x32_bf16 v[70:73], v[178:181], v[230:233], v[70:73]
	v_mfma_f32_16x16x32_bf16 v[66:69], v[186:189], v[230:233], v[66:69]
	v_mfma_f32_16x16x32_bf16 v[118:121], v[182:185], v[210:213], v[118:121]
	v_mfma_f32_16x16x32_bf16 v[114:117], v[202:205], v[210:213], v[114:117]
	v_mfma_f32_16x16x32_bf16 v[102:105], v[182:185], v[218:221], v[102:105]
	v_mfma_f32_16x16x32_bf16 v[98:101], v[202:205], v[218:221], v[98:101]
	v_mfma_f32_16x16x32_bf16 v[86:89], v[182:185], v[226:229], v[86:89]
	v_mfma_f32_16x16x32_bf16 v[82:85], v[202:205], v[226:229], v[82:85]
	v_mfma_f32_16x16x32_bf16 v[70:73], v[182:185], v[234:237], v[70:73]
	v_mfma_f32_16x16x32_bf16 v[66:69], v[202:205], v[234:237], v[66:69]
	s_setprio 0
	s_barrier
	s_add_i32 s4, s4, s40
	v_lshl_add_u64 v[238:239], s[34:35], 0, v[152:153]
	s_mov_b32 m0, s4
	ds_read_b128 v[206:209], v164 offset:16384
	ds_read_b128 v[210:213], v164 offset:17408
	ds_read_b128 v[214:217], v164 offset:18432
	ds_read_b128 v[218:221], v164 offset:19456
	ds_read_b128 v[222:225], v164 offset:20480
	ds_read_b128 v[226:229], v164 offset:21504
	ds_read_b128 v[230:233], v164 offset:22528
	ds_read_b128 v[234:237], v164 offset:23552
	global_load_lds_dwordx4 v[238:239], off
	s_add_i32 m0, s4, 0x2000
	s_add_u32 s4, s34, 0x40000
	v_lshl_add_u64 v[240:241], s[34:35], 0, v[150:151]
	s_addc_u32 s5, s35, 0
	s_add_i32 s28, s65, s40
	global_load_lds_dwordx4 v[240:241], off
	v_lshl_add_u64 v[242:243], s[4:5], 0, v[152:153]
	s_mov_b32 m0, s28
	v_lshl_add_u64 v[244:245], s[36:37], 0, v[150:151]
	global_load_lds_dwordx4 v[242:243], off
	v_lshl_add_u64 v[242:243], s[4:5], 0, v[150:151]
	s_add_i32 m0, s28, 0x2000
	s_nop 0
	global_load_lds_dwordx4 v[242:243], off
	v_lshl_add_u64 v[242:243], s[36:37], 0, v[152:153]
	s_mov_b32 m0, s41
	s_nop 0
	global_load_lds_dwordx4 v[242:243], off
	s_mov_b32 m0, s42
	s_nop 0
	global_load_lds_dwordx4 v[244:245], off
	s_waitcnt vmcnt(9)
	s_waitcnt lgkmcnt(0)
	s_barrier
	s_setprio 1
	s_waitcnt lgkmcnt(0)
	v_mfma_f32_16x16x32_bf16 v[62:65], v[158:161], v[206:209], v[62:65]
	v_mfma_f32_16x16x32_bf16 v[58:61], v[170:173], v[206:209], v[58:61]
	v_mfma_f32_16x16x32_bf16 v[46:49], v[158:161], v[214:217], v[46:49]
	v_mfma_f32_16x16x32_bf16 v[42:45], v[170:173], v[214:217], v[42:45]
	v_mfma_f32_16x16x32_bf16 v[30:33], v[158:161], v[222:225], v[30:33]
	v_mfma_f32_16x16x32_bf16 v[26:29], v[170:173], v[222:225], v[26:29]
	v_mfma_f32_16x16x32_bf16 v[14:17], v[158:161], v[230:233], v[14:17]
	v_mfma_f32_16x16x32_bf16 v[10:13], v[170:173], v[230:233], v[10:13]
	v_mfma_f32_16x16x32_bf16 v[62:65], v[166:169], v[210:213], v[62:65]
	v_mfma_f32_16x16x32_bf16 v[58:61], v[174:177], v[210:213], v[58:61]
	v_mfma_f32_16x16x32_bf16 v[46:49], v[166:169], v[218:221], v[46:49]
	v_mfma_f32_16x16x32_bf16 v[42:45], v[174:177], v[218:221], v[42:45]
	v_mfma_f32_16x16x32_bf16 v[30:33], v[166:169], v[226:229], v[30:33]
	v_mfma_f32_16x16x32_bf16 v[26:29], v[174:177], v[226:229], v[26:29]
	v_mfma_f32_16x16x32_bf16 v[14:17], v[166:169], v[234:237], v[14:17]
	v_mfma_f32_16x16x32_bf16 v[10:13], v[174:177], v[234:237], v[10:13]
	s_setprio 0
	s_setprio 1
	v_mfma_f32_16x16x32_bf16 v[54:57], v[178:181], v[206:209], v[54:57]
	v_mfma_f32_16x16x32_bf16 v[50:53], v[186:189], v[206:209], v[50:53]
	v_mfma_f32_16x16x32_bf16 v[38:41], v[178:181], v[214:217], v[38:41]
	v_mfma_f32_16x16x32_bf16 v[34:37], v[186:189], v[214:217], v[34:37]
	v_mfma_f32_16x16x32_bf16 v[22:25], v[178:181], v[222:225], v[22:25]
	v_mfma_f32_16x16x32_bf16 v[18:21], v[186:189], v[222:225], v[18:21]
	v_mfma_f32_16x16x32_bf16 v[6:9], v[178:181], v[230:233], v[6:9]
	v_mfma_f32_16x16x32_bf16 v[2:5], v[186:189], v[230:233], v[2:5]
	v_mfma_f32_16x16x32_bf16 v[54:57], v[182:185], v[210:213], v[54:57]
	v_mfma_f32_16x16x32_bf16 v[50:53], v[202:205], v[210:213], v[50:53]
	v_mfma_f32_16x16x32_bf16 v[38:41], v[182:185], v[218:221], v[38:41]
	v_mfma_f32_16x16x32_bf16 v[34:37], v[202:205], v[218:221], v[34:37]
	v_mfma_f32_16x16x32_bf16 v[22:25], v[182:185], v[226:229], v[22:25]
	v_mfma_f32_16x16x32_bf16 v[18:21], v[202:205], v[226:229], v[18:21]
	v_mfma_f32_16x16x32_bf16 v[6:9], v[182:185], v[234:237], v[6:9]
	v_mfma_f32_16x16x32_bf16 v[2:5], v[202:205], v[234:237], v[2:5]
	s_setprio 0
	s_barrier
; #define PG8_STAGE(bufoff, gbase, voff) do { _Pragma("unroll") for (int _i = 0; _i < 2; ++_i) \
;         __builtin_amdgcn_global_load_lds((const unsigned*)((const char*)(gbase) + (voff)[_i]), (PG8_LAS unsigned*)(lds + (bufoff) + ldsw + _i * 8192), 16, 0, 0); } while (0)
; #define PG8_LDA(dst, b, h) do { _Pragma("unroll") for (int m = 0; m < 4; ++m) _Pragma("unroll") for (int k = 0; k < 2; ++k) dst[m][k] = *(const PG8_LAS bf16x8*)(lds + PG8_SA(b, h) + aoff + m * 2048 + k * 1024); } while (0)
; #define PG8_LDB(dst, b, h) do { _Pragma("unroll") for (int n = 0; n < 2; ++n) _Pragma("unroll") for (int k = 0; k < 2; ++k) dst[n][k] = *(const PG8_LAS bf16x8*)(lds + PG8_SB(b, h) + boff + n * 2048 + k * 1024); } while (0)
; #define PG8_MMA(ai, bj, At, Bt) do { __builtin_amdgcn_s_setprio(1); _Pragma("unroll") for (int m = 0; m < 4; ++m) _Pragma("unroll") for (int n = 0; n < 2; ++n) _Pragma("unroll") for (int k = 0; k < 2; ++k) \
;         acc[ai][bj][m][n] = __builtin_amdgcn_mfma_f32_16x16x32_bf16(Bt[n][k], At[m][k], acc[ai][bj][m][n], 0, 0, 0); __builtin_amdgcn_s_setprio(0); } while (0)
; #define PG8_WAIT_V(n) asm volatile("s_waitcnt vmcnt(" #n ")" ::: "memory")
; #define PG8_WAIT_L(n) asm volatile("s_waitcnt lgkmcnt(" #n ")" ::: "memory")
; #define PG8_BAR __builtin_amdgcn_s_barrier()
; #define PG8_SCHED __builtin_amdgcn_sched_barrier(0)
; template <class Epi, class Sched, bool ALIGN_EPI = false, bool SP2 = false>
; __device__ __forceinline__ void gemm_phase(PG8_LAS unsigned char* lds, const Gemm g, const Sched& S, const Epi& E) {
;     ...
;             PG8_LDB(B0, 1, 0); PG8_LDB(B1, 1, 1); PG8_SCHED; PG8_LDA(At, 1, 0); PG8_STAGE(PG8_SA(0, 1), a2 + hstep, voffA);
;             PG8_WAIT_V(8); PG8_WAIT_L(0); PG8_BAR; PG8_MMA(0, 0, At, B0); PG8_MMA(0, 1, At, B1); PG8_BAR; PG8_SCHED;
	s_add_i32 s28, 0, 0x18000
	v_add_u32_e32 v165, s28, v162
	s_add_i32 s29, 0, 0x1c000
	ds_read_b128 v[158:161], v165
	ds_read_b128 v[166:169], v165 offset:1024
	ds_read_b128 v[170:173], v165 offset:2048
	ds_read_b128 v[174:177], v165 offset:3072
	v_add_u32_e32 v165, s29, v162
	ds_read_b128 v[178:181], v165
	ds_read_b128 v[182:185], v165 offset:1024
	ds_read_b128 v[186:189], v165 offset:2048
	ds_read_b128 v[202:205], v165 offset:3072
	s_add_u32 s4, s36, 0x40000
	s_addc_u32 s5, s37, 0
	s_mov_b32 m0, s43
	v_lshl_add_u64 v[246:247], s[4:5], 0, v[152:153]
	ds_read_b128 v[206:209], v164 offset:32768
	ds_read_b128 v[210:213], v164 offset:33792
	ds_read_b128 v[214:217], v164 offset:34816
	ds_read_b128 v[218:221], v164 offset:35840
	ds_read_b128 v[222:225], v164 offset:36864
	ds_read_b128 v[226:229], v164 offset:37888
	ds_read_b128 v[230:233], v164 offset:38912
	ds_read_b128 v[234:237], v164 offset:39936
	global_load_lds_dwordx4 v[246:247], off
	v_lshl_add_u64 v[246:247], s[4:5], 0, v[150:151]
	s_mov_b32 m0, s44
	s_nop 0
	global_load_lds_dwordx4 v[246:247], off
	s_waitcnt vmcnt(9)
	s_waitcnt lgkmcnt(0)
	s_barrier
	s_setprio 1
	s_waitcnt lgkmcnt(0)
	v_mfma_f32_16x16x32_bf16 v[126:129], v[158:161], v[206:209], v[126:129]
	v_mfma_f32_16x16x32_bf16 v[122:125], v[170:173], v[206:209], v[122:125]
	v_mfma_f32_16x16x32_bf16 v[110:113], v[158:161], v[214:217], v[110:113]
	v_mfma_f32_16x16x32_bf16 v[106:109], v[170:173], v[214:217], v[106:109]
	v_mfma_f32_16x16x32_bf16 v[94:97], v[158:161], v[222:225], v[94:97]
	v_mfma_f32_16x16x32_bf16 v[90:93], v[170:173], v[222:225], v[90:93]
	v_mfma_f32_16x16x32_bf16 v[78:81], v[158:161], v[230:233], v[78:81]
	v_mfma_f32_16x16x32_bf16 v[74:77], v[170:173], v[230:233], v[74:77]
	v_mfma_f32_16x16x32_bf16 v[126:129], v[166:169], v[210:213], v[126:129]
	v_mfma_f32_16x16x32_bf16 v[122:125], v[174:177], v[210:213], v[122:125]
	v_mfma_f32_16x16x32_bf16 v[110:113], v[166:169], v[218:221], v[110:113]
	v_mfma_f32_16x16x32_bf16 v[106:109], v[174:177], v[218:221], v[106:109]
	v_mfma_f32_16x16x32_bf16 v[94:97], v[166:169], v[226:229], v[94:97]
	v_mfma_f32_16x16x32_bf16 v[90:93], v[174:177], v[226:229], v[90:93]
	v_mfma_f32_16x16x32_bf16 v[78:81], v[166:169], v[234:237], v[78:81]
	v_mfma_f32_16x16x32_bf16 v[74:77], v[174:177], v[234:237], v[74:77]
	s_setprio 0
	s_setprio 1
	v_mfma_f32_16x16x32_bf16 v[118:121], v[178:181], v[206:209], v[118:121]
	v_mfma_f32_16x16x32_bf16 v[114:117], v[186:189], v[206:209], v[114:117]
	v_mfma_f32_16x16x32_bf16 v[102:105], v[178:181], v[214:217], v[102:105]
	v_mfma_f32_16x16x32_bf16 v[98:101], v[186:189], v[214:217], v[98:101]
	v_mfma_f32_16x16x32_bf16 v[86:89], v[178:181], v[222:225], v[86:89]
	v_mfma_f32_16x16x32_bf16 v[82:85], v[186:189], v[222:225], v[82:85]
	v_mfma_f32_16x16x32_bf16 v[70:73], v[178:181], v[230:233], v[70:73]
	v_mfma_f32_16x16x32_bf16 v[66:69], v[186:189], v[230:233], v[66:69]
	v_mfma_f32_16x16x32_bf16 v[118:121], v[182:185], v[210:213], v[118:121]
	v_mfma_f32_16x16x32_bf16 v[114:117], v[202:205], v[210:213], v[114:117]
	v_mfma_f32_16x16x32_bf16 v[102:105], v[182:185], v[218:221], v[102:105]
	v_mfma_f32_16x16x32_bf16 v[98:101], v[202:205], v[218:221], v[98:101]
	v_mfma_f32_16x16x32_bf16 v[86:89], v[182:185], v[226:229], v[86:89]
	v_mfma_f32_16x16x32_bf16 v[82:85], v[202:205], v[226:229], v[82:85]
	v_mfma_f32_16x16x32_bf16 v[70:73], v[182:185], v[234:237], v[70:73]
	v_mfma_f32_16x16x32_bf16 v[66:69], v[202:205], v[234:237], v[66:69]
	s_setprio 0
	s_barrier
; #define PG8_STAGE(bufoff, gbase, voff) do { _Pragma("unroll") for (int _i = 0; _i < 2; ++_i) \
;         __builtin_amdgcn_global_load_lds((const unsigned*)((const char*)(gbase) + (voff)[_i]), (PG8_LAS unsigned*)(lds + (bufoff) + ldsw + _i * 8192), 16, 0, 0); } while (0)
; #define PG8_LDA(dst, b, h) do { _Pragma("unroll") for (int m = 0; m < 4; ++m) _Pragma("unroll") for (int k = 0; k < 2; ++k) dst[m][k] = *(const PG8_LAS bf16x8*)(lds + PG8_SA(b, h) + aoff + m * 2048 + k * 1024); } while (0)
; #define PG8_MMA(ai, bj, At, Bt) do { __builtin_amdgcn_s_setprio(1); _Pragma("unroll") for (int m = 0; m < 4; ++m) _Pragma("unroll") for (int n = 0; n < 2; ++n) _Pragma("unroll") for (int k = 0; k < 2; ++k) \
;         acc[ai][bj][m][n] = __builtin_amdgcn_mfma_f32_16x16x32_bf16(Bt[n][k], At[m][k], acc[ai][bj][m][n], 0, 0, 0); __builtin_amdgcn_s_setprio(0); } while (0)
; #define PG8_WAIT_V(n) asm volatile("s_waitcnt vmcnt(" #n ")" ::: "memory")
; #define PG8_WAIT_L(n) asm volatile("s_waitcnt lgkmcnt(" #n ")" ::: "memory")
; #define PG8_BAR __builtin_amdgcn_s_barrier()
; #define PG8_SCHED __builtin_amdgcn_sched_barrier(0)
; template <class Epi, class Sched, bool ALIGN_EPI = false, bool SP2 = false>
; __device__ __forceinline__ void gemm_phase(PG8_LAS unsigned char* lds, const Gemm g, const Sched& S, const Epi& E) {
;     ...
;             PG8_LDA(At, 1, 1); PG8_STAGE(PG8_SB(1, 0), b3, voffB); PG8_STAGE(PG8_SB(1, 1), b3 + hstep, voffB); PG8_STAGE(PG8_SA(1, 0), a3, voffA);
;             PG8_WAIT_V(8); PG8_WAIT_L(0); PG8_BAR; PG8_MMA(1, 0, At, B0); PG8_MMA(1, 1, At, B1); PG8_BAR; PG8_SCHED;
;     ...
;         if constexpr (ALIGN_EPI) { if (wr == 0) PG8_BAR; }
	s_add_i32 s4, s28, s40
	v_lshl_add_u64 v[238:239], v[238:239], 0, s[62:63]
	s_mov_b32 m0, s4
	ds_read_b128 v[206:209], v164 offset:49152
	ds_read_b128 v[210:213], v164 offset:50176
	ds_read_b128 v[214:217], v164 offset:51200
	ds_read_b128 v[218:221], v164 offset:52224
	ds_read_b128 v[222:225], v164 offset:53248
	ds_read_b128 v[226:229], v164 offset:54272
	ds_read_b128 v[230:233], v164 offset:55296
	ds_read_b128 v[234:237], v164 offset:56320
	global_load_lds_dwordx4 v[238:239], off
	s_add_i32 m0, s4, 0x2000
	s_add_u32 s4, s34, 0x40080
	v_lshl_add_u64 v[238:239], v[240:241], 0, s[62:63]
	s_addc_u32 s5, s35, 0
	s_add_i32 s28, s29, s40
	global_load_lds_dwordx4 v[238:239], off
	v_lshl_add_u64 v[238:239], s[4:5], 0, v[152:153]
	s_mov_b32 m0, s28
	s_nop 0
	global_load_lds_dwordx4 v[238:239], off
	v_lshl_add_u64 v[238:239], s[4:5], 0, v[150:151]
	s_add_i32 m0, s28, 0x2000
	s_nop 0
	global_load_lds_dwordx4 v[238:239], off
	v_lshl_add_u64 v[238:239], v[242:243], 0, s[62:63]
	s_mov_b32 m0, s47
	s_nop 0
	global_load_lds_dwordx4 v[238:239], off
	v_lshl_add_u64 v[238:239], v[244:245], 0, s[62:63]
	s_mov_b32 m0, s48
	s_nop 0
	global_load_lds_dwordx4 v[238:239], off
	s_waitcnt vmcnt(8)
	s_waitcnt lgkmcnt(0)
	s_barrier
	s_setprio 1
	s_waitcnt lgkmcnt(0)
	v_mfma_f32_16x16x32_bf16 v[62:65], v[158:161], v[206:209], v[62:65]
	v_mfma_f32_16x16x32_bf16 v[58:61], v[170:173], v[206:209], v[58:61]
	v_mfma_f32_16x16x32_bf16 v[46:49], v[158:161], v[214:217], v[46:49]
	v_mfma_f32_16x16x32_bf16 v[42:45], v[170:173], v[214:217], v[42:45]
	v_mfma_f32_16x16x32_bf16 v[30:33], v[158:161], v[222:225], v[30:33]
	v_mfma_f32_16x16x32_bf16 v[26:29], v[170:173], v[222:225], v[26:29]
	v_mfma_f32_16x16x32_bf16 v[14:17], v[158:161], v[230:233], v[14:17]
	v_mfma_f32_16x16x32_bf16 v[10:13], v[170:173], v[230:233], v[10:13]
	v_mfma_f32_16x16x32_bf16 v[62:65], v[166:169], v[210:213], v[62:65]
	v_mfma_f32_16x16x32_bf16 v[58:61], v[174:177], v[210:213], v[58:61]
	v_mfma_f32_16x16x32_bf16 v[46:49], v[166:169], v[218:221], v[46:49]
	v_mfma_f32_16x16x32_bf16 v[42:45], v[174:177], v[218:221], v[42:45]
	v_mfma_f32_16x16x32_bf16 v[30:33], v[166:169], v[226:229], v[30:33]
	v_mfma_f32_16x16x32_bf16 v[26:29], v[174:177], v[226:229], v[26:29]
	v_mfma_f32_16x16x32_bf16 v[14:17], v[166:169], v[234:237], v[14:17]
	v_mfma_f32_16x16x32_bf16 v[10:13], v[174:177], v[234:237], v[10:13]
	s_setprio 0
	s_setprio 1
	v_mfma_f32_16x16x32_bf16 v[54:57], v[178:181], v[206:209], v[54:57]
	v_mfma_f32_16x16x32_bf16 v[50:53], v[186:189], v[206:209], v[50:53]
	v_mfma_f32_16x16x32_bf16 v[38:41], v[178:181], v[214:217], v[38:41]
	v_mfma_f32_16x16x32_bf16 v[34:37], v[186:189], v[214:217], v[34:37]
	v_mfma_f32_16x16x32_bf16 v[22:25], v[178:181], v[222:225], v[22:25]
	v_mfma_f32_16x16x32_bf16 v[18:21], v[186:189], v[222:225], v[18:21]
	v_mfma_f32_16x16x32_bf16 v[6:9], v[178:181], v[230:233], v[6:9]
	v_mfma_f32_16x16x32_bf16 v[2:5], v[186:189], v[230:233], v[2:5]
	v_mfma_f32_16x16x32_bf16 v[54:57], v[182:185], v[210:213], v[54:57]
	v_mfma_f32_16x16x32_bf16 v[50:53], v[202:205], v[210:213], v[50:53]
	v_mfma_f32_16x16x32_bf16 v[38:41], v[182:185], v[218:221], v[38:41]
	v_mfma_f32_16x16x32_bf16 v[34:37], v[202:205], v[218:221], v[34:37]
	v_mfma_f32_16x16x32_bf16 v[22:25], v[182:185], v[226:229], v[22:25]
	v_mfma_f32_16x16x32_bf16 v[18:21], v[202:205], v[226:229], v[18:21]
	v_mfma_f32_16x16x32_bf16 v[6:9], v[182:185], v[234:237], v[6:9]
	v_mfma_f32_16x16x32_bf16 v[2:5], v[202:205], v[234:237], v[2:5]
	s_setprio 0
	s_barrier
	s_add_i32 s64, s64, 2
	s_add_u32 s54, s54, 0x100
	s_addc_u32 s55, s55, 0
	s_cmp_gt_u32 s64, 13
	s_mov_b64 s[28:29], s[30:31]
	s_cbranch_scc0 .LBB0_1680
	s_and_b64 vcc, exec, s[18:19]
	s_cbranch_vccz .LBB0_1683
	s_barrier

; #define PG8_STAGE(bufoff, gbase, voff) do { _Pragma("unroll") for (int _i = 0; _i < 2; ++_i) \
;         __builtin_amdgcn_global_load_lds((const unsigned*)((const char*)(gbase) + (voff)[_i]), (PG8_LAS unsigned*)(lds + (bufoff) + ldsw + _i * 8192), 16, 0, 0); } while (0)
; #define PG8_LDA(dst, b, h) do { _Pragma("unroll") for (int m = 0; m < 4; ++m) _Pragma("unroll") for (int k = 0; k < 2; ++k) dst[m][k] = *(const PG8_LAS bf16x8*)(lds + PG8_SA(b, h) + aoff + m * 2048 + k * 1024); } while (0)
; #define PG8_LDB(dst, b, h) do { _Pragma("unroll") for (int n = 0; n < 2; ++n) _Pragma("unroll") for (int k = 0; k < 2; ++k) dst[n][k] = *(const PG8_LAS bf16x8*)(lds + PG8_SB(b, h) + boff + n * 2048 + k * 1024); } while (0)
; #define PG8_BAR __builtin_amdgcn_s_barrier()
; #define PG8_SCHED __builtin_amdgcn_sched_barrier(0)
; template <class Epi, class Sched, bool ALIGN_EPI = false, bool SP2 = false>
; __device__ __forceinline__ void gemm_phase(PG8_LAS unsigned char* lds, const Gemm g, const Sched& S, const Epi& E) {
;     ...
;         const bool has_next = S.next(ui + 1, nxt);
;         const char* nA = has_next ? (const char*)g.A + (size_t)nxt.pm * tstep : cA; const char* nB = has_next ? (const char*)g.Bt + (size_t)nxt.pn * tstep : cB;
;         for (int t = 0; t < nt; t += 2) {
;             const bool last = (t == nt - 2);
;             const char* a1 = cA + (size_t)(t + 1) * kstep;
;             const char* a2 = last ? nA : cA + (size_t)(t + 2) * kstep; const char* b2 = last ? nB : cB + (size_t)(t + 2) * kstep;
;             const char* a3 = a2 + kstep; const char* b3 = b2 + kstep;
;             if (last && has_next) S.a_ready(nxt);
;             if constexpr (SP2) {
;             PG8_LDB(B0, 0, 0); PG8_LDB(B1, 0, 1); PG8_SCHED; PG8_LDA(At, 0, 0); PG8_STAGE(PG8_SA(1, 1), a1 + hstep, voffA);
;     ...
;         if constexpr (ALIGN_EPI) { if (wr == 0) PG8_BAR; }
;         if constexpr (!Epi::AFTER_DRAIN) { E(acc, cur, wr, wc, fr, fq); S.done(cur); }
;         if (!has_next) break;
; #pragma unroll
;         for (int a = 0; a < 2; ++a)
; #pragma unroll
;             for (int b = 0; b < 2; ++b)
; #pragma unroll
;                 for (int m = 0; m < 4; ++m)
; #pragma unroll
;                     for (int n = 0; n < 2; ++n) acc[a][b][m][n] = (f32x4){0.f, 0.f, 0.f, 0.f};
.LBB0_1889:
	s_add_u32 s48, s24, 0x100
	v_mov_b32_e32 v2, 0
	s_addc_u32 s49, s25, 0
	s_mov_b32 s50, -2
	s_waitcnt lgkmcnt(0)
	v_mov_b32_e32 v3, v2
	v_mov_b32_e32 v4, v2
	v_mov_b32_e32 v5, v2
	v_mov_b32_e32 v6, v2
	v_mov_b32_e32 v7, v2
	v_mov_b32_e32 v8, v2
	v_mov_b32_e32 v9, v2
	v_mov_b32_e32 v18, v2
	v_mov_b32_e32 v19, v2
	v_mov_b32_e32 v20, v2
	v_mov_b32_e32 v21, v2
	v_mov_b32_e32 v22, v2
	v_mov_b32_e32 v23, v2
	v_mov_b32_e32 v24, v2
	v_mov_b32_e32 v25, v2
	v_mov_b32_e32 v34, v2
	v_mov_b32_e32 v35, v2
	v_mov_b32_e32 v36, v2
	v_mov_b32_e32 v37, v2
	v_mov_b32_e32 v38, v2
	v_mov_b32_e32 v39, v2
	v_mov_b32_e32 v40, v2
	v_mov_b32_e32 v41, v2
	v_mov_b32_e32 v50, v2
	v_mov_b32_e32 v51, v2
	v_mov_b32_e32 v52, v2
	v_mov_b32_e32 v53, v2
	v_mov_b32_e32 v54, v2
	v_mov_b32_e32 v55, v2
	v_mov_b32_e32 v56, v2
	v_mov_b32_e32 v57, v2
	v_mov_b32_e32 v10, v2
	v_mov_b32_e32 v11, v2
	v_mov_b32_e32 v12, v2
	v_mov_b32_e32 v13, v2
	v_mov_b32_e32 v14, v2
	v_mov_b32_e32 v15, v2
	v_mov_b32_e32 v16, v2
	v_mov_b32_e32 v17, v2
	v_mov_b32_e32 v26, v2
	v_mov_b32_e32 v27, v2
	v_mov_b32_e32 v28, v2
	v_mov_b32_e32 v29, v2
	v_mov_b32_e32 v30, v2
	v_mov_b32_e32 v31, v2
	v_mov_b32_e32 v32, v2
	v_mov_b32_e32 v33, v2
	v_mov_b32_e32 v42, v2
	v_mov_b32_e32 v43, v2
	v_mov_b32_e32 v44, v2
	v_mov_b32_e32 v45, v2
	v_mov_b32_e32 v46, v2
	v_mov_b32_e32 v47, v2
	v_mov_b32_e32 v48, v2
	v_mov_b32_e32 v49, v2
	v_mov_b32_e32 v58, v2
	v_mov_b32_e32 v59, v2
	v_mov_b32_e32 v60, v2
	v_mov_b32_e32 v61, v2
	v_mov_b32_e32 v62, v2
	v_mov_b32_e32 v63, v2
	v_mov_b32_e32 v64, v2
	v_mov_b32_e32 v65, v2
	v_mov_b32_e32 v66, v2
	v_mov_b32_e32 v67, v2
	v_mov_b32_e32 v68, v2
	v_mov_b32_e32 v69, v2
	v_mov_b32_e32 v70, v2
	v_mov_b32_e32 v71, v2
	v_mov_b32_e32 v72, v2
	v_mov_b32_e32 v73, v2
	v_mov_b32_e32 v82, v2
	v_mov_b32_e32 v83, v2
	v_mov_b32_e32 v84, v2
	v_mov_b32_e32 v85, v2
	v_mov_b32_e32 v86, v2
	v_mov_b32_e32 v87, v2
	v_mov_b32_e32 v88, v2
	v_mov_b32_e32 v89, v2
	v_mov_b32_e32 v98, v2
	v_mov_b32_e32 v99, v2
	v_mov_b32_e32 v100, v2
	v_mov_b32_e32 v101, v2
	v_mov_b32_e32 v102, v2
	v_mov_b32_e32 v103, v2
	v_mov_b32_e32 v104, v2
	v_mov_b32_e32 v105, v2
	v_mov_b32_e32 v114, v2
	v_mov_b32_e32 v115, v2
	v_mov_b32_e32 v116, v2
	v_mov_b32_e32 v117, v2
	v_mov_b32_e32 v118, v2
	v_mov_b32_e32 v119, v2
	v_mov_b32_e32 v120, v2
	v_mov_b32_e32 v121, v2
	v_mov_b32_e32 v74, v2
	v_mov_b32_e32 v75, v2
	v_mov_b32_e32 v76, v2
	v_mov_b32_e32 v77, v2
	v_mov_b32_e32 v78, v2
	v_mov_b32_e32 v79, v2
	v_mov_b32_e32 v80, v2
	v_mov_b32_e32 v81, v2
	v_mov_b32_e32 v90, v2
	v_mov_b32_e32 v91, v2
	v_mov_b32_e32 v92, v2
	v_mov_b32_e32 v93, v2
	v_mov_b32_e32 v94, v2
	v_mov_b32_e32 v95, v2
	v_mov_b32_e32 v96, v2
	v_mov_b32_e32 v97, v2
	v_mov_b32_e32 v106, v2
	v_mov_b32_e32 v107, v2
	v_mov_b32_e32 v108, v2
	v_mov_b32_e32 v109, v2
	v_mov_b32_e32 v110, v2
	v_mov_b32_e32 v111, v2
	v_mov_b32_e32 v112, v2
	v_mov_b32_e32 v113, v2
	v_mov_b32_e32 v122, v2
	v_mov_b32_e32 v123, v2
	v_mov_b32_e32 v124, v2
	v_mov_b32_e32 v125, v2
	v_mov_b32_e32 v126, v2
	v_mov_b32_e32 v127, v2
	v_mov_b32_e32 v128, v2
	v_mov_b32_e32 v129, v2
	v_lshrrev_b32_e32 v249, 4, v190
	v_lshlrev_b32_e32 v249, 11, v249
	v_bfe_u32 v250, v190, 2, 2
	v_lshl_add_u32 v249, v250, 7, v249
	v_and_b32_e32 v250, 3, v190
	v_lshl_add_u32 v249, v250, 2, v249
	s_lshl_b32 s100, s35, 3
	s_lshl_b32 s101, s47, 19
	s_add_u32 s100, s100, s101
	s_lshl_b32 s101, s46, 9
	s_add_u32 s100, s100, s101
	v_add_u32_e32 v249, s100, v249
.LBB0_1890:
	s_add_u32 s24, s22, 0x100
	s_addc_u32 s25, s23, 0
	s_add_i32 s4, 0, 0x10000
	s_cmp_eq_u32 s50, 40
	s_cselect_b32 s29, s11, s25
	s_cselect_b32 s28, s10, s24
	v_add_u32_e32 v165, s4, v162
	s_cselect_b32 s27, s21, s49
	s_cselect_b32 s26, s20, s48
	s_add_i32 s51, 0, 0x14000
	ds_read_b128 v[158:161], v165
	ds_read_b128 v[166:169], v165 offset:1024
	ds_read_b128 v[170:173], v165 offset:2048
	ds_read_b128 v[174:177], v165 offset:3072
	v_add_u32_e32 v165, s51, v162
	ds_read_b128 v[178:181], v165
	ds_read_b128 v[182:185], v165 offset:1024
	ds_read_b128 v[186:189], v165 offset:2048
	ds_read_b128 v[202:205], v165 offset:3072
	v_lshl_add_u64 v[238:239], s[22:23], 0, v[154:155]
	s_add_i32 m0, s35, 0xc000
	ds_read_b128 v[206:209], v164
	ds_read_b128 v[210:213], v164 offset:1024
	ds_read_b128 v[214:217], v164 offset:2048
	ds_read_b128 v[218:221], v164 offset:3072
	ds_read_b128 v[222:225], v164 offset:4096
	ds_read_b128 v[226:229], v164 offset:5120
	ds_read_b128 v[230:233], v164 offset:6144
	ds_read_b128 v[234:237], v164 offset:7168
	global_load_lds_dwordx4 v[238:239], off
	v_lshl_add_u64 v[238:239], s[22:23], 0, v[156:157]
	s_add_i32 m0, s35, 0xe000
	s_nop 0
	global_load_lds_dwordx4 v[238:239], off
	s_bfe_u32 s100, s50, 0x30001
	s_lshl_b32 s100, s100, 16
	v_add_u32_e32 v250, s100, v249
	global_load_dword v248, v250, s[14:15]
	s_waitcnt vmcnt(9)
	s_waitcnt lgkmcnt(0)
	s_barrier
; #define PG8_STAGE(bufoff, gbase, voff) do { _Pragma("unroll") for (int _i = 0; _i < 2; ++_i) \
;         __builtin_amdgcn_global_load_lds((const unsigned*)((const char*)(gbase) + (voff)[_i]), (PG8_LAS unsigned*)(lds + (bufoff) + ldsw + _i * 8192), 16, 0, 0); } while (0)
; #define PG8_LDA(dst, b, h) do { _Pragma("unroll") for (int m = 0; m < 4; ++m) _Pragma("unroll") for (int k = 0; k < 2; ++k) dst[m][k] = *(const PG8_LAS bf16x8*)(lds + PG8_SA(b, h) + aoff + m * 2048 + k * 1024); } while (0)
; #define PG8_LDB(dst, b, h) do { _Pragma("unroll") for (int n = 0; n < 2; ++n) _Pragma("unroll") for (int k = 0; k < 2; ++k) dst[n][k] = *(const PG8_LAS bf16x8*)(lds + PG8_SB(b, h) + boff + n * 2048 + k * 1024); } while (0)
; #define PG8_MMA(ai, bj, At, Bt) do { __builtin_amdgcn_s_setprio(1); _Pragma("unroll") for (int m = 0; m < 4; ++m) _Pragma("unroll") for (int n = 0; n < 2; ++n) _Pragma("unroll") for (int k = 0; k < 2; ++k) \
;         acc[ai][bj][m][n] = __builtin_amdgcn_mfma_f32_16x16x32_bf16(Bt[n][k], At[m][k], acc[ai][bj][m][n], 0, 0, 0); __builtin_amdgcn_s_setprio(0); } while (0)
; #define PG8_WAIT_V(n) asm volatile("s_waitcnt vmcnt(" #n ")" ::: "memory")
; #define PG8_WAIT_L(n) asm volatile("s_waitcnt lgkmcnt(" #n ")" ::: "memory")
; #define PG8_BAR __builtin_amdgcn_s_barrier()
; #define PG8_SCHED __builtin_amdgcn_sched_barrier(0)
; template <class Epi, class Sched, bool ALIGN_EPI = false, bool SP2 = false>
; __device__ __forceinline__ void gemm_phase(PG8_LAS unsigned char* lds, const Gemm g, const Sched& S, const Epi& E) {
;     ...
;             PG8_LDB(B0, 0, 0); PG8_LDB(B1, 0, 1); PG8_SCHED; PG8_LDA(At, 0, 0); PG8_STAGE(PG8_SA(1, 1), a1 + hstep, voffA);
;             PG8_WAIT_V(8); PG8_WAIT_L(0); PG8_BAR; PG8_MMA(0, 0, At, B0); PG8_MMA(0, 1, At, B1); PG8_BAR; PG8_SCHED;
;             PG8_LDA(At, 0, 1); PG8_STAGE(PG8_SB(0, 0), b2, voffB); PG8_STAGE(PG8_SB(0, 1), b2 + hstep, voffB); PG8_STAGE(PG8_SA(0, 0), a2, voffA);
;             PG8_WAIT_V(8); PG8_WAIT_L(0); PG8_BAR; PG8_MMA(1, 0, At, B0); PG8_MMA(1, 1, At, B1); PG8_BAR; PG8_SCHED;
	s_setprio 1
	s_waitcnt lgkmcnt(0)
	v_mfma_f32_16x16x32_bf16 v[126:129], v[158:161], v[206:209], v[126:129]
	v_mfma_f32_16x16x32_bf16 v[122:125], v[170:173], v[206:209], v[122:125]
	v_mfma_f32_16x16x32_bf16 v[110:113], v[158:161], v[214:217], v[110:113]
	v_mfma_f32_16x16x32_bf16 v[106:109], v[170:173], v[214:217], v[106:109]
	v_mfma_f32_16x16x32_bf16 v[94:97], v[158:161], v[222:225], v[94:97]
	v_mfma_f32_16x16x32_bf16 v[90:93], v[170:173], v[222:225], v[90:93]
	v_mfma_f32_16x16x32_bf16 v[78:81], v[158:161], v[230:233], v[78:81]
	v_mfma_f32_16x16x32_bf16 v[74:77], v[170:173], v[230:233], v[74:77]
	v_mfma_f32_16x16x32_bf16 v[126:129], v[166:169], v[210:213], v[126:129]
	v_mfma_f32_16x16x32_bf16 v[122:125], v[174:177], v[210:213], v[122:125]
	v_mfma_f32_16x16x32_bf16 v[110:113], v[166:169], v[218:221], v[110:113]
	v_mfma_f32_16x16x32_bf16 v[106:109], v[174:177], v[218:221], v[106:109]
	v_mfma_f32_16x16x32_bf16 v[94:97], v[166:169], v[226:229], v[94:97]
	v_mfma_f32_16x16x32_bf16 v[90:93], v[174:177], v[226:229], v[90:93]
	v_mfma_f32_16x16x32_bf16 v[78:81], v[166:169], v[234:237], v[78:81]
	v_mfma_f32_16x16x32_bf16 v[74:77], v[174:177], v[234:237], v[74:77]
	s_setprio 0
	s_setprio 1
	v_mfma_f32_16x16x32_bf16 v[118:121], v[178:181], v[206:209], v[118:121]
	v_mfma_f32_16x16x32_bf16 v[114:117], v[186:189], v[206:209], v[114:117]
	v_mfma_f32_16x16x32_bf16 v[102:105], v[178:181], v[214:217], v[102:105]
	v_mfma_f32_16x16x32_bf16 v[98:101], v[186:189], v[214:217], v[98:101]
	v_mfma_f32_16x16x32_bf16 v[86:89], v[178:181], v[222:225], v[86:89]
	v_mfma_f32_16x16x32_bf16 v[82:85], v[186:189], v[222:225], v[82:85]
	v_mfma_f32_16x16x32_bf16 v[70:73], v[178:181], v[230:233], v[70:73]
	v_mfma_f32_16x16x32_bf16 v[66:69], v[186:189], v[230:233], v[66:69]
	v_mfma_f32_16x16x32_bf16 v[118:121], v[182:185], v[210:213], v[118:121]
	v_mfma_f32_16x16x32_bf16 v[114:117], v[202:205], v[210:213], v[114:117]
	v_mfma_f32_16x16x32_bf16 v[102:105], v[182:185], v[218:221], v[102:105]
	v_mfma_f32_16x16x32_bf16 v[98:101], v[202:205], v[218:221], v[98:101]
	v_mfma_f32_16x16x32_bf16 v[86:89], v[182:185], v[226:229], v[86:89]
	v_mfma_f32_16x16x32_bf16 v[82:85], v[202:205], v[226:229], v[82:85]
	v_mfma_f32_16x16x32_bf16 v[70:73], v[182:185], v[234:237], v[70:73]
	v_mfma_f32_16x16x32_bf16 v[66:69], v[202:205], v[234:237], v[66:69]
	s_setprio 0
	s_barrier
	s_add_i32 s4, s4, s34
	v_lshl_add_u64 v[238:239], s[26:27], 0, v[152:153]
	s_mov_b32 m0, s4
	ds_read_b128 v[206:209], v164 offset:16384
	ds_read_b128 v[210:213], v164 offset:17408
	ds_read_b128 v[214:217], v164 offset:18432
	ds_read_b128 v[218:221], v164 offset:19456
	ds_read_b128 v[222:225], v164 offset:20480
	ds_read_b128 v[226:229], v164 offset:21504
	ds_read_b128 v[230:233], v164 offset:22528
	ds_read_b128 v[234:237], v164 offset:23552
	global_load_lds_dwordx4 v[238:239], off
	s_add_i32 m0, s4, 0x2000
	s_add_u32 s4, s26, 0xb0000
	v_lshl_add_u64 v[240:241], s[26:27], 0, v[150:151]
	s_addc_u32 s5, s27, 0
	s_add_i32 s22, s51, s34
	global_load_lds_dwordx4 v[240:241], off
	v_lshl_add_u64 v[242:243], s[4:5], 0, v[152:153]
	s_mov_b32 m0, s22
	v_lshl_add_u64 v[244:245], s[28:29], 0, v[150:151]
	global_load_lds_dwordx4 v[242:243], off
	v_lshl_add_u64 v[242:243], s[4:5], 0, v[150:151]
	s_add_i32 m0, s22, 0x2000
	s_nop 0
	global_load_lds_dwordx4 v[242:243], off
	v_lshl_add_u64 v[242:243], s[28:29], 0, v[152:153]
	s_mov_b32 m0, s35
	s_nop 0
	global_load_lds_dwordx4 v[242:243], off
	s_mov_b32 m0, s36
	s_nop 0
	global_load_lds_dwordx4 v[244:245], off
	s_waitcnt vmcnt(9)
	s_waitcnt lgkmcnt(0)
	s_barrier
	s_setprio 1
	s_waitcnt lgkmcnt(0)
	v_mfma_f32_16x16x32_bf16 v[62:65], v[158:161], v[206:209], v[62:65]
	v_mfma_f32_16x16x32_bf16 v[58:61], v[170:173], v[206:209], v[58:61]
	v_mfma_f32_16x16x32_bf16 v[46:49], v[158:161], v[214:217], v[46:49]
	v_mfma_f32_16x16x32_bf16 v[42:45], v[170:173], v[214:217], v[42:45]
	v_mfma_f32_16x16x32_bf16 v[30:33], v[158:161], v[222:225], v[30:33]
	v_mfma_f32_16x16x32_bf16 v[26:29], v[170:173], v[222:225], v[26:29]
	v_mfma_f32_16x16x32_bf16 v[14:17], v[158:161], v[230:233], v[14:17]
	v_mfma_f32_16x16x32_bf16 v[10:13], v[170:173], v[230:233], v[10:13]
	v_mfma_f32_16x16x32_bf16 v[62:65], v[166:169], v[210:213], v[62:65]
	v_mfma_f32_16x16x32_bf16 v[58:61], v[174:177], v[210:213], v[58:61]
	v_mfma_f32_16x16x32_bf16 v[46:49], v[166:169], v[218:221], v[46:49]
	v_mfma_f32_16x16x32_bf16 v[42:45], v[174:177], v[218:221], v[42:45]
	v_mfma_f32_16x16x32_bf16 v[30:33], v[166:169], v[226:229], v[30:33]
	v_mfma_f32_16x16x32_bf16 v[26:29], v[174:177], v[226:229], v[26:29]
	v_mfma_f32_16x16x32_bf16 v[14:17], v[166:169], v[234:237], v[14:17]
	v_mfma_f32_16x16x32_bf16 v[10:13], v[174:177], v[234:237], v[10:13]
	s_setprio 0
	s_setprio 1
	v_mfma_f32_16x16x32_bf16 v[54:57], v[178:181], v[206:209], v[54:57]
	v_mfma_f32_16x16x32_bf16 v[50:53], v[186:189], v[206:209], v[50:53]
	v_mfma_f32_16x16x32_bf16 v[38:41], v[178:181], v[214:217], v[38:41]
	v_mfma_f32_16x16x32_bf16 v[34:37], v[186:189], v[214:217], v[34:37]
	v_mfma_f32_16x16x32_bf16 v[22:25], v[178:181], v[222:225], v[22:25]
	v_mfma_f32_16x16x32_bf16 v[18:21], v[186:189], v[222:225], v[18:21]
	v_mfma_f32_16x16x32_bf16 v[6:9], v[178:181], v[230:233], v[6:9]
	v_mfma_f32_16x16x32_bf16 v[2:5], v[186:189], v[230:233], v[2:5]
	v_mfma_f32_16x16x32_bf16 v[54:57], v[182:185], v[210:213], v[54:57]
	v_mfma_f32_16x16x32_bf16 v[50:53], v[202:205], v[210:213], v[50:53]
	v_mfma_f32_16x16x32_bf16 v[38:41], v[182:185], v[218:221], v[38:41]
	v_mfma_f32_16x16x32_bf16 v[34:37], v[202:205], v[218:221], v[34:37]
	v_mfma_f32_16x16x32_bf16 v[22:25], v[182:185], v[226:229], v[22:25]
	v_mfma_f32_16x16x32_bf16 v[18:21], v[202:205], v[226:229], v[18:21]
	v_mfma_f32_16x16x32_bf16 v[6:9], v[182:185], v[234:237], v[6:9]
	v_mfma_f32_16x16x32_bf16 v[2:5], v[202:205], v[234:237], v[2:5]
	s_setprio 0
	s_barrier
; #define PG8_STAGE(bufoff, gbase, voff) do { _Pragma("unroll") for (int _i = 0; _i < 2; ++_i) \
;         __builtin_amdgcn_global_load_lds((const unsigned*)((const char*)(gbase) + (voff)[_i]), (PG8_LAS unsigned*)(lds + (bufoff) + ldsw + _i * 8192), 16, 0, 0); } while (0)
; #define PG8_LDA(dst, b, h) do { _Pragma("unroll") for (int m = 0; m < 4; ++m) _Pragma("unroll") for (int k = 0; k < 2; ++k) dst[m][k] = *(const PG8_LAS bf16x8*)(lds + PG8_SA(b, h) + aoff + m * 2048 + k * 1024); } while (0)
; #define PG8_LDB(dst, b, h) do { _Pragma("unroll") for (int n = 0; n < 2; ++n) _Pragma("unroll") for (int k = 0; k < 2; ++k) dst[n][k] = *(const PG8_LAS bf16x8*)(lds + PG8_SB(b, h) + boff + n * 2048 + k * 1024); } while (0)
; #define PG8_MMA(ai, bj, At, Bt) do { __builtin_amdgcn_s_setprio(1); _Pragma("unroll") for (int m = 0; m < 4; ++m) _Pragma("unroll") for (int n = 0; n < 2; ++n) _Pragma("unroll") for (int k = 0; k < 2; ++k) \
;         acc[ai][bj][m][n] = __builtin_amdgcn_mfma_f32_16x16x32_bf16(Bt[n][k], At[m][k], acc[ai][bj][m][n], 0, 0, 0); __builtin_amdgcn_s_setprio(0); } while (0)
; #define PG8_WAIT_V(n) asm volatile("s_waitcnt vmcnt(" #n ")" ::: "memory")
; #define PG8_WAIT_L(n) asm volatile("s_waitcnt lgkmcnt(" #n ")" ::: "memory")
; #define PG8_BAR __builtin_amdgcn_s_barrier()
; #define PG8_SCHED __builtin_amdgcn_sched_barrier(0)
; template <class Epi, class Sched, bool ALIGN_EPI = false, bool SP2 = false>
; __device__ __forceinline__ void gemm_phase(PG8_LAS unsigned char* lds, const Gemm g, const Sched& S, const Epi& E) {
;     ...
;             PG8_LDB(B0, 1, 0); PG8_LDB(B1, 1, 1); PG8_SCHED; PG8_LDA(At, 1, 0); PG8_STAGE(PG8_SA(0, 1), a2 + hstep, voffA);
;             PG8_WAIT_V(8); PG8_WAIT_L(0); PG8_BAR; PG8_MMA(0, 0, At, B0); PG8_MMA(0, 1, At, B1); PG8_BAR; PG8_SCHED;
	s_add_i32 s22, 0, 0x18000
	v_add_u32_e32 v165, s22, v162
	s_add_i32 s23, 0, 0x1c000
	ds_read_b128 v[158:161], v165
	ds_read_b128 v[166:169], v165 offset:1024
	ds_read_b128 v[170:173], v165 offset:2048
	ds_read_b128 v[174:177], v165 offset:3072
	v_add_u32_e32 v165, s23, v162
	ds_read_b128 v[178:181], v165
	ds_read_b128 v[182:185], v165 offset:1024
	ds_read_b128 v[186:189], v165 offset:2048
	ds_read_b128 v[202:205], v165 offset:3072
	s_add_u32 s4, s28, 0xb0000
	s_addc_u32 s5, s29, 0
	s_mov_b32 m0, s37
	v_lshl_add_u64 v[246:247], s[4:5], 0, v[152:153]
	ds_read_b128 v[206:209], v164 offset:32768
	ds_read_b128 v[210:213], v164 offset:33792
	ds_read_b128 v[214:217], v164 offset:34816
	ds_read_b128 v[218:221], v164 offset:35840
	ds_read_b128 v[222:225], v164 offset:36864
	ds_read_b128 v[226:229], v164 offset:37888
	ds_read_b128 v[230:233], v164 offset:38912
	ds_read_b128 v[234:237], v164 offset:39936
	global_load_lds_dwordx4 v[246:247], off
	v_lshl_add_u64 v[246:247], s[4:5], 0, v[150:151]
	s_mov_b32 m0, s38
	s_nop 0
	global_load_lds_dwordx4 v[246:247], off
	s_waitcnt vmcnt(9)
	s_waitcnt lgkmcnt(0)
	s_barrier
	s_setprio 1
	s_waitcnt lgkmcnt(0)
	v_mfma_f32_16x16x32_bf16 v[126:129], v[158:161], v[206:209], v[126:129]
	v_mfma_f32_16x16x32_bf16 v[122:125], v[170:173], v[206:209], v[122:125]
	v_mfma_f32_16x16x32_bf16 v[110:113], v[158:161], v[214:217], v[110:113]
	v_mfma_f32_16x16x32_bf16 v[106:109], v[170:173], v[214:217], v[106:109]
	v_mfma_f32_16x16x32_bf16 v[94:97], v[158:161], v[222:225], v[94:97]
	v_mfma_f32_16x16x32_bf16 v[90:93], v[170:173], v[222:225], v[90:93]
	v_mfma_f32_16x16x32_bf16 v[78:81], v[158:161], v[230:233], v[78:81]
	v_mfma_f32_16x16x32_bf16 v[74:77], v[170:173], v[230:233], v[74:77]
	v_mfma_f32_16x16x32_bf16 v[126:129], v[166:169], v[210:213], v[126:129]
	v_mfma_f32_16x16x32_bf16 v[122:125], v[174:177], v[210:213], v[122:125]
	v_mfma_f32_16x16x32_bf16 v[110:113], v[166:169], v[218:221], v[110:113]
	v_mfma_f32_16x16x32_bf16 v[106:109], v[174:177], v[218:221], v[106:109]
	v_mfma_f32_16x16x32_bf16 v[94:97], v[166:169], v[226:229], v[94:97]
	v_mfma_f32_16x16x32_bf16 v[90:93], v[174:177], v[226:229], v[90:93]
	v_mfma_f32_16x16x32_bf16 v[78:81], v[166:169], v[234:237], v[78:81]
	v_mfma_f32_16x16x32_bf16 v[74:77], v[174:177], v[234:237], v[74:77]
	s_setprio 0
	s_setprio 1
	v_mfma_f32_16x16x32_bf16 v[118:121], v[178:181], v[206:209], v[118:121]
	v_mfma_f32_16x16x32_bf16 v[114:117], v[186:189], v[206:209], v[114:117]
	v_mfma_f32_16x16x32_bf16 v[102:105], v[178:181], v[214:217], v[102:105]
	v_mfma_f32_16x16x32_bf16 v[98:101], v[186:189], v[214:217], v[98:101]
	v_mfma_f32_16x16x32_bf16 v[86:89], v[178:181], v[222:225], v[86:89]
	v_mfma_f32_16x16x32_bf16 v[82:85], v[186:189], v[222:225], v[82:85]
	v_mfma_f32_16x16x32_bf16 v[70:73], v[178:181], v[230:233], v[70:73]
	v_mfma_f32_16x16x32_bf16 v[66:69], v[186:189], v[230:233], v[66:69]
	v_mfma_f32_16x16x32_bf16 v[118:121], v[182:185], v[210:213], v[118:121]
	v_mfma_f32_16x16x32_bf16 v[114:117], v[202:205], v[210:213], v[114:117]
	v_mfma_f32_16x16x32_bf16 v[102:105], v[182:185], v[218:221], v[102:105]
	v_mfma_f32_16x16x32_bf16 v[98:101], v[202:205], v[218:221], v[98:101]
	v_mfma_f32_16x16x32_bf16 v[86:89], v[182:185], v[226:229], v[86:89]
	v_mfma_f32_16x16x32_bf16 v[82:85], v[202:205], v[226:229], v[82:85]
	v_mfma_f32_16x16x32_bf16 v[70:73], v[182:185], v[234:237], v[70:73]
	v_mfma_f32_16x16x32_bf16 v[66:69], v[202:205], v[234:237], v[66:69]
	s_setprio 0
	s_barrier
; #define PG8_STAGE(bufoff, gbase, voff) do { _Pragma("unroll") for (int _i = 0; _i < 2; ++_i) \
;         __builtin_amdgcn_global_load_lds((const unsigned*)((const char*)(gbase) + (voff)[_i]), (PG8_LAS unsigned*)(lds + (bufoff) + ldsw + _i * 8192), 16, 0, 0); } while (0)
; #define PG8_LDA(dst, b, h) do { _Pragma("unroll") for (int m = 0; m < 4; ++m) _Pragma("unroll") for (int k = 0; k < 2; ++k) dst[m][k] = *(const PG8_LAS bf16x8*)(lds + PG8_SA(b, h) + aoff + m * 2048 + k * 1024); } while (0)
; #define PG8_MMA(ai, bj, At, Bt) do { __builtin_amdgcn_s_setprio(1); _Pragma("unroll") for (int m = 0; m < 4; ++m) _Pragma("unroll") for (int n = 0; n < 2; ++n) _Pragma("unroll") for (int k = 0; k < 2; ++k) \
;         acc[ai][bj][m][n] = __builtin_amdgcn_mfma_f32_16x16x32_bf16(Bt[n][k], At[m][k], acc[ai][bj][m][n], 0, 0, 0); __builtin_amdgcn_s_setprio(0); } while (0)
; #define PG8_WAIT_V(n) asm volatile("s_waitcnt vmcnt(" #n ")" ::: "memory")
; #define PG8_WAIT_L(n) asm volatile("s_waitcnt lgkmcnt(" #n ")" ::: "memory")
; #define PG8_BAR __builtin_amdgcn_s_barrier()
; #define PG8_SCHED __builtin_amdgcn_sched_barrier(0)
; template <class Epi, class Sched, bool ALIGN_EPI = false, bool SP2 = false>
; __device__ __forceinline__ void gemm_phase(PG8_LAS unsigned char* lds, const Gemm g, const Sched& S, const Epi& E) {
;     ...
;             PG8_LDA(At, 1, 1); PG8_STAGE(PG8_SB(1, 0), b3, voffB); PG8_STAGE(PG8_SB(1, 1), b3 + hstep, voffB); PG8_STAGE(PG8_SA(1, 0), a3, voffA);
;             PG8_WAIT_V(8); PG8_WAIT_L(0); PG8_BAR; PG8_MMA(1, 0, At, B0); PG8_MMA(1, 1, At, B1); PG8_BAR; PG8_SCHED;
;     ...
;         if constexpr (ALIGN_EPI) { if (wr == 0) PG8_BAR; }
	s_add_i32 s4, s22, s34
	v_lshl_add_u64 v[238:239], v[238:239], 0, s[62:63]
	s_mov_b32 m0, s4
	ds_read_b128 v[206:209], v164 offset:49152
	ds_read_b128 v[210:213], v164 offset:50176
	ds_read_b128 v[214:217], v164 offset:51200
	ds_read_b128 v[218:221], v164 offset:52224
	ds_read_b128 v[222:225], v164 offset:53248
	ds_read_b128 v[226:229], v164 offset:54272
	ds_read_b128 v[230:233], v164 offset:55296
	ds_read_b128 v[234:237], v164 offset:56320
	global_load_lds_dwordx4 v[238:239], off
	s_add_i32 m0, s4, 0x2000
	s_add_u32 s4, s26, 0xb0080
	v_lshl_add_u64 v[238:239], v[240:241], 0, s[62:63]
	s_addc_u32 s5, s27, 0
	s_add_i32 s22, s23, s34
	global_load_lds_dwordx4 v[238:239], off
	v_lshl_add_u64 v[238:239], s[4:5], 0, v[152:153]
	s_mov_b32 m0, s22
	s_nop 0
	global_load_lds_dwordx4 v[238:239], off
	v_lshl_add_u64 v[238:239], s[4:5], 0, v[150:151]
	s_add_i32 m0, s22, 0x2000
	s_nop 0
	global_load_lds_dwordx4 v[238:239], off
	v_lshl_add_u64 v[238:239], v[242:243], 0, s[62:63]
	s_mov_b32 m0, s41
	s_nop 0
	global_load_lds_dwordx4 v[238:239], off
	v_lshl_add_u64 v[238:239], v[244:245], 0, s[62:63]
	s_mov_b32 m0, s42
	s_nop 0
	global_load_lds_dwordx4 v[238:239], off
	s_waitcnt vmcnt(8)
	s_waitcnt lgkmcnt(0)
	s_barrier
	s_setprio 1
	s_waitcnt lgkmcnt(0)
	v_mfma_f32_16x16x32_bf16 v[62:65], v[158:161], v[206:209], v[62:65]
	v_mfma_f32_16x16x32_bf16 v[58:61], v[170:173], v[206:209], v[58:61]
	v_mfma_f32_16x16x32_bf16 v[46:49], v[158:161], v[214:217], v[46:49]
	v_mfma_f32_16x16x32_bf16 v[42:45], v[170:173], v[214:217], v[42:45]
	v_mfma_f32_16x16x32_bf16 v[30:33], v[158:161], v[222:225], v[30:33]
	v_mfma_f32_16x16x32_bf16 v[26:29], v[170:173], v[222:225], v[26:29]
	v_mfma_f32_16x16x32_bf16 v[14:17], v[158:161], v[230:233], v[14:17]
	v_mfma_f32_16x16x32_bf16 v[10:13], v[170:173], v[230:233], v[10:13]
	v_mfma_f32_16x16x32_bf16 v[62:65], v[166:169], v[210:213], v[62:65]
	v_mfma_f32_16x16x32_bf16 v[58:61], v[174:177], v[210:213], v[58:61]
	v_mfma_f32_16x16x32_bf16 v[46:49], v[166:169], v[218:221], v[46:49]
	v_mfma_f32_16x16x32_bf16 v[42:45], v[174:177], v[218:221], v[42:45]
	v_mfma_f32_16x16x32_bf16 v[30:33], v[166:169], v[226:229], v[30:33]
	v_mfma_f32_16x16x32_bf16 v[26:29], v[174:177], v[226:229], v[26:29]
	v_mfma_f32_16x16x32_bf16 v[14:17], v[166:169], v[234:237], v[14:17]
	v_mfma_f32_16x16x32_bf16 v[10:13], v[174:177], v[234:237], v[10:13]
	s_setprio 0
	s_setprio 1
	v_mfma_f32_16x16x32_bf16 v[54:57], v[178:181], v[206:209], v[54:57]
	v_mfma_f32_16x16x32_bf16 v[50:53], v[186:189], v[206:209], v[50:53]
	v_mfma_f32_16x16x32_bf16 v[38:41], v[178:181], v[214:217], v[38:41]
	v_mfma_f32_16x16x32_bf16 v[34:37], v[186:189], v[214:217], v[34:37]
	v_mfma_f32_16x16x32_bf16 v[22:25], v[178:181], v[222:225], v[22:25]
	v_mfma_f32_16x16x32_bf16 v[18:21], v[186:189], v[222:225], v[18:21]
	v_mfma_f32_16x16x32_bf16 v[6:9], v[178:181], v[230:233], v[6:9]
	v_mfma_f32_16x16x32_bf16 v[2:5], v[186:189], v[230:233], v[2:5]
	v_mfma_f32_16x16x32_bf16 v[54:57], v[182:185], v[210:213], v[54:57]
	v_mfma_f32_16x16x32_bf16 v[50:53], v[202:205], v[210:213], v[50:53]
	v_mfma_f32_16x16x32_bf16 v[38:41], v[182:185], v[218:221], v[38:41]
	v_mfma_f32_16x16x32_bf16 v[34:37], v[202:205], v[218:221], v[34:37]
	v_mfma_f32_16x16x32_bf16 v[22:25], v[182:185], v[226:229], v[22:25]
	v_mfma_f32_16x16x32_bf16 v[18:21], v[202:205], v[226:229], v[18:21]
	v_mfma_f32_16x16x32_bf16 v[6:9], v[182:185], v[234:237], v[6:9]
	v_mfma_f32_16x16x32_bf16 v[2:5], v[202:205], v[234:237], v[2:5]
	s_setprio 0
	s_barrier
	s_add_i32 s50, s50, 2
	s_add_u32 s48, s48, 0x100
	s_addc_u32 s49, s49, 0
	s_cmp_gt_u32 s50, 41
	s_mov_b64 s[22:23], s[24:25]
	s_cbranch_scc0 .LBB0_1890
	s_and_b64 vcc, exec, s[18:19]
	s_cbranch_vccz .LBB0_1893
	s_barrier
